# K-tile LDS-DMA rebalanced between halves: leading waves issue all 16 K pieces (own + partner, +0x2000), trailing waves issue only V pieces; vmcnt 8/4 and 4/4
# baseline (speedup 1.0000x reference)
; __device__ __forceinline__ int v_rd_base(int lane) { return ((lane & 3) << 3) | (((lane >> 2) & 3) << 6) | (((lane >> 4) & 1) << 5) | (((lane >> 5) & 1) << 8); }
; #define LAS3 __attribute__((address_space(3)))
; template <int LDO>
; __device__ __forceinline__ void attn_unit_dv(const bf16_t* __restrict__ Qb, const bf16_t* __restrict__ Kh, const bf16_t* __restrict__ Vh, bf16_t* __restrict__ Ob, int NT, char* lds, LAS3 unsigned char* ldsl) {
;   const int tid = threadIdx.x, lane = tid & 63, r32 = lane & 31, hi = lane >> 5; const int wid = __builtin_amdgcn_readfirstlane(tid >> 6);
;   float* ws = (float*)(lds + DV_WS) + wid * 64; float* li_l = ws; float* al_l = ws + 32;
;   float m_reg = -1e30f, l_reg = 0.f; f32x16 o[8] = {}; bf16x8 qr[8];
;   const unsigned koff0 = (unsigned)((8 * wid + (lane >> 4)) * (LDK * 2) + (((lane & 15) ^ (lane >> 4)) << 4));
;   const int hf = wid >> 2;
;   unsigned voff0;
;   { const int lc = (4 * wid) & 15, b = lc * 1024 + 16 * lane, sub = b >> 9, e = (b & 511) >> 1;
;     const int kk = (sub >> 2) * 8 + (e >> 5), c = (sub & 3) * 32 + (e & 31), k = (kk & ~0xC) | ((kk & 4) << 1) | ((kk & 8) >> 1);
;     voff0 = (unsigned)(k * (LDV2 * 2) + (hf * 128 + c) * 2); }
;   LAS3 unsigned char* kdst = ldsl + DV_K0 + wid * 2048;
;   LAS3 unsigned char* vdst = ldsl + DV_V0 + hf * 16384 + ((4 * wid) & 15) * 1024;
;     ...
;   if (wid >= 4) __builtin_amdgcn_s_setprio(1);
;   DMA_KV(0, 0);
;   const bf16_t* Qw = Qb + (long)(wid * QBLK + r32) * LDQ + hi * 8;
; #pragma unroll
;   for (int d0 = 0; d0 < 8; ++d0) qr[d0] = ld8(Qw + d0 * 16);
;   const int vb0 = (int)(uintptr_t)(lds + DV_V0) + v_rd_base(lane);
;   asm volatile("s_waitcnt vmcnt(0) lgkmcnt(0)" ::: "memory"); __builtin_amdgcn_s_barrier(); asm volatile("" ::: "memory");
.LBB0_642:
	v_readfirstlane_b32 s99, v194
	s_bfe_u32 s31, s28, 0x10009
	s_bfe_u32 s30, s28, 0x20007
	s_lshl_b32 s1, s31, 3
	s_lshl_b32 s4, s30, 1
	s_bfe_u32 s29, s28, 0x10006
	s_or_b32 s1, s1, s4
	s_or_b32 s1, s1, s29
	s_lshl_b32 s33, s1, 22
	s_lshl_b32 s1, s28, 8
	s_and_b32 s34, s1, 0x3f00
	s_lshl_b32 s1, s34, 8
	s_or_b32 s1, s1, s33
	s_add_u32 s68, s42, s1
	s_addc_u32 s69, s43, 0
	s_add_u32 s78, s44, s33
	s_addc_u32 s79, s45, 0
	s_lshl_b32 s1, s30, 23
	s_lshl_b32 s4, s31, 25
	s_or_b32 s80, s4, s1
	s_add_u32 s82, s48, s80
	s_addc_u32 s83, s49, 0
	s_lshr_b32 s1, s0, 6
	s_lshr_b32 s35, s0, 2
	s_lshl_b32 s4, s1, 11
	s_and_b32 s98, s1, 1
	s_lshl_b32 s98, s98, 7
	s_or_b32 s98, s98, s4
	s_and_b32 s35, s35, 48
	s_and_b32 s84, s0, 0xffffff00
	s_lshl_b32 s66, s0, 6
	v_or_b32_e32 v3, s35, v226
	v_or_b32_e32 v0, s84, v222
	s_add_i32 s35, s4, 0
	v_xor_b32_e32 v2, s98, v221
	s_and_b32 s67, s66, 0x3000
	v_lshl_add_u32 v4, v3, 9, v0
	s_and_b32 s66, s66, 0x7fffc000
	s_mov_b32 m0, s35
	v_xor_b32_e32 v0, 64, v2
	s_add_i32 s66, s66, 0
	global_load_lds_dwordx4 v2, s[78:79]
	v_lshl_add_u64 v[6:7], s[78:79], 0, v[0:1]
	s_mov_b64 s[78:79], 0x400
	s_add_i32 s66, s66, s67
	v_lshl_add_u64 v[6:7], v[6:7], 0, s[78:79]
	s_add_i32 m0, s35, 0x400
	v_mov_b32_e32 v5, v1
	global_load_lds_dwordx4 v[6:7], off
	v_lshl_add_u64 v[6:7], s[82:83], 0, v[4:5]
	s_add_i32 m0, s66, 0x8000
	s_mov_b64 s[78:79], 0x80
	global_load_lds_dwordx4 v4, s[82:83]
	v_lshl_add_u64 v[4:5], v[6:7], 0, s[78:79]
	s_add_i32 m0, s66, 0x8400
	s_mov_b64 s[78:79], 0x800
	global_load_lds_dwordx4 v[4:5], off
	v_lshl_add_u64 v[4:5], v[6:7], 0, s[78:79]
	s_add_i32 m0, s66, 0x8800
	s_mov_b64 s[78:79], 0x880
	global_load_lds_dwordx4 v[4:5], off
	v_lshl_add_u64 v[4:5], v[6:7], 0, s[78:79]
	s_add_i32 m0, s66, 0x8c00
	s_lshl_b32 s4, s1, 5
	global_load_lds_dwordx4 v[4:5], off
	v_or_b32_e32 v4, s4, v198
	v_mov_b32_e32 v5, v1
	v_lshlrev_b64 v[4:5], 8, v[4:5]
	v_lshl_add_u64 v[4:5], s[68:69], 0, v[4:5]
	v_lshl_add_u64 v[4:5], v[4:5], 0, v[196:197]
	global_load_dwordx4 v[162:165], v[4:5], off
	global_load_dwordx4 v[166:169], v[4:5], off offset:32
	global_load_dwordx4 v[170:173], v[4:5], off offset:64
	global_load_dwordx4 v[174:177], v[4:5], off offset:96
	global_load_dwordx4 v[178:181], v[4:5], off offset:128
	global_load_dwordx4 v[182:185], v[4:5], off offset:160
	global_load_dwordx4 v[186:189], v[4:5], off offset:192
	global_load_dwordx4 v[190:193], v[4:5], off offset:224
	s_and_b32 s0, s0, 0x3fffffc0
	s_lshl_b32 s0, s0, 2
	s_add_i32 s67, s0, 0
	s_add_i32 s67, s67, 0x20000
	s_add_u32 s0, s33, 0x2fe04400
	s_addc_u32 s1, 0, 0
	v_lshl_or_b32 v3, v3, 9, v227
	v_lshl_add_u64 v[204:205], s[0:1], 0, v[0:1]
	s_add_u32 s0, s33, 0x2fe04000
	s_mov_b32 s81, s5
	v_add_u32_e32 v4, s84, v3
	v_mov_b32_e32 v5, v1
	s_addc_u32 s1, 0, 0
	v_mov_b32_e32 v3, v1
	s_waitcnt vmcnt(0)
	v_mov_b32_e32 v14, v1
	v_mov_b32_e32 v15, v1
	s_waitcnt vmcnt(0) lgkmcnt(0)
	s_barrier
	v_lshl_add_u64 v[202:203], s[80:81], 0, v[4:5]
	v_lshl_add_u64 v[206:207], s[0:1], 0, v[2:3]
	v_mov_b32_e32 v0, v1
	v_mov_b32_e32 v2, v1
	v_mov_b32_e32 v4, v1
	v_mov_b32_e32 v6, v1
	v_mov_b32_e32 v7, v1
	v_mov_b32_e32 v8, v1
	v_mov_b32_e32 v9, v1
	v_mov_b32_e32 v10, v1
	v_mov_b32_e32 v11, v1
	v_mov_b32_e32 v12, v1
	v_mov_b32_e32 v13, v1
	v_mov_b64_e32 v[128:129], v[14:15]
	v_mov_b64_e32 v[112:113], v[14:15]
	v_mov_b64_e32 v[96:97], v[14:15]
	v_mov_b64_e32 v[80:81], v[14:15]
	v_mov_b64_e32 v[64:65], v[14:15]
	v_mov_b64_e32 v[48:49], v[14:15]
	v_mov_b64_e32 v[32:33], v[14:15]
	v_mov_b64_e32 v[126:127], v[12:13]
	v_mov_b64_e32 v[124:125], v[10:11]
	v_mov_b64_e32 v[122:123], v[8:9]
	v_mov_b64_e32 v[120:121], v[6:7]
	v_mov_b64_e32 v[118:119], v[4:5]
	v_mov_b64_e32 v[116:117], v[2:3]
	v_mov_b64_e32 v[114:115], v[0:1]
	v_mov_b64_e32 v[110:111], v[12:13]
	v_mov_b64_e32 v[108:109], v[10:11]
	v_mov_b64_e32 v[106:107], v[8:9]
	v_mov_b64_e32 v[104:105], v[6:7]
	v_mov_b64_e32 v[102:103], v[4:5]
	v_mov_b64_e32 v[100:101], v[2:3]
	v_mov_b64_e32 v[98:99], v[0:1]
	v_mov_b64_e32 v[94:95], v[12:13]
	v_mov_b64_e32 v[92:93], v[10:11]
	v_mov_b64_e32 v[90:91], v[8:9]
	v_mov_b64_e32 v[88:89], v[6:7]
	v_mov_b64_e32 v[86:87], v[4:5]
	v_mov_b64_e32 v[84:85], v[2:3]
	v_mov_b64_e32 v[82:83], v[0:1]
	v_mov_b64_e32 v[78:79], v[12:13]
	v_mov_b64_e32 v[76:77], v[10:11]
	v_mov_b64_e32 v[74:75], v[8:9]
	v_mov_b64_e32 v[72:73], v[6:7]
	v_mov_b64_e32 v[70:71], v[4:5]
	v_mov_b64_e32 v[68:69], v[2:3]
	v_mov_b64_e32 v[66:67], v[0:1]
	v_mov_b64_e32 v[62:63], v[12:13]
	v_mov_b64_e32 v[60:61], v[10:11]
	v_mov_b64_e32 v[58:59], v[8:9]
	v_mov_b64_e32 v[56:57], v[6:7]
	v_mov_b64_e32 v[54:55], v[4:5]
	v_mov_b64_e32 v[52:53], v[2:3]
	v_mov_b64_e32 v[50:51], v[0:1]
	v_mov_b64_e32 v[46:47], v[12:13]
	v_mov_b64_e32 v[44:45], v[10:11]
	v_mov_b64_e32 v[42:43], v[8:9]
	v_mov_b64_e32 v[40:41], v[6:7]
	v_mov_b64_e32 v[38:39], v[4:5]
	v_mov_b64_e32 v[36:37], v[2:3]
	v_mov_b64_e32 v[34:35], v[0:1]
	v_mov_b64_e32 v[30:31], v[12:13]
	v_mov_b64_e32 v[28:29], v[10:11]
	v_mov_b64_e32 v[26:27], v[8:9]
	v_mov_b64_e32 v[24:25], v[6:7]
	v_mov_b64_e32 v[22:23], v[4:5]
	v_mov_b64_e32 v[20:21], v[2:3]
	v_mov_b64_e32 v[18:19], v[0:1]
	v_mov_b64_e32 v[16:17], v[14:15]
	v_readlane_b32 s70, v244, 42
	v_lshl_add_u32 v228, v198, 2, s67
	s_mov_b32 s68, 0
	v_mov_b32_e32 v230, 0
	v_mov_b32_e32 v229, 0xf149f2ca
	v_mov_b64_e32 v[14:15], v[12:13]
	v_mov_b64_e32 v[12:13], v[10:11]
	v_mov_b64_e32 v[10:11], v[8:9]
	v_mov_b64_e32 v[8:9], v[6:7]
	v_mov_b64_e32 v[6:7], v[4:5]
	v_mov_b64_e32 v[4:5], v[2:3]
	v_mov_b64_e32 v[2:3], v[0:1]
	v_readlane_b32 s71, v244, 43
	s_mov_b32 s98, 0
	s_mov_b32 s100, 1
	s_mov_b32 s101, 2
	s_cmpk_lt_u32 s99, 0x100
	s_cbranch_scc1 .Lpl_pre_e
	s_mov_b32 s0, 0x8000
	s_add_i32 s33, s66, s0
	v_lshl_add_u64 v[254:255], s[22:23], 0, v[202:203]
	s_mov_b64 s[0:1], 0x33e08000
	v_lshl_add_u64 v[254:255], v[254:255], 0, s[0:1]
	s_add_i32 m0, s33, 0x8000
	s_mov_b64 s[0:1], 0x80
	global_load_lds_dwordx4 v[254:255], off
	v_lshl_add_u64 v[254:255], v[254:255], 0, s[0:1]
	s_add_i32 m0, s33, 0x8400
	s_mov_b64 s[0:1], 0x780
	global_load_lds_dwordx4 v[254:255], off
	v_lshl_add_u64 v[254:255], v[254:255], 0, s[0:1]
	s_add_i32 m0, s33, 0x8800
	s_mov_b64 s[0:1], 0x80
	global_load_lds_dwordx4 v[254:255], off
	v_lshl_add_u64 v[254:255], v[254:255], 0, s[0:1]
	s_add_i32 m0, s33, 0x8c00
	s_nop 0
	global_load_lds_dwordx4 v[254:255], off
	s_barrier
	s_branch .Lpl_top

; template <bool WIN>
; __device__ __forceinline__ void partialSM(f32x16& p0, f32x16& p1, float& m_reg, float& mn, float& alpha) {
;   constexpr float C = SCALE * 1.4426950408889634f;
;   float pmax = p0[0];
; #pragma unroll
;   for (int r = 1; r < 16; ++r) pmax = fmaxf(pmax, p0[r]);
; #pragma unroll
;   for (int r = 0; r < 16; ++r) pmax = fmaxf(pmax, p1[r]);
;   { auto rr = __builtin_amdgcn_permlane32_swap(__float_as_uint(pmax), __float_as_uint(pmax), false, false);
;     pmax = fmaxf(__uint_as_float(rr[0]), __uint_as_float(rr[1])); }
;   if (__builtin_expect(__all(pmax - m_reg <= THR / SCALE), 1)) { mn = m_reg; alpha = 1.f; }
;   else { mn = fmaxf(m_reg, pmax); alpha = __builtin_amdgcn_exp2f((m_reg - mn) * C); m_reg = mn; }
;   float mnC = -mn * C;
; #pragma unroll
;   for (int r = 0; r < 16; ++r) p0[r] = fmaf(p0[r], C, mnC);
; #pragma unroll
;   for (int r = 0; r < 16; ++r) p1[r] = fmaf(p1[r], C, mnC);
; #pragma unroll
;   for (int r = 0; r < 16; ++r) p0[r] = __builtin_amdgcn_exp2f(p0[r]);
; }
; __device__ __forceinline__ void finishSM(f32x16& p0, f32x16& p1, float alpha, float& l_reg, bf16x8& pa0, bf16x8& pa1, bf16x8& pa2, bf16x8& pa3) {
; #pragma unroll
;   for (int r = 0; r < 16; ++r) p1[r] = __builtin_amdgcn_exp2f(p1[r]);
;   float ps = 0;
; #pragma unroll
;   for (int r = 0; r < 16; ++r) ps += p0[r];
; #pragma unroll
;   for (int r = 0; r < 16; ++r) ps += p1[r];
;   { auto rr = __builtin_amdgcn_permlane32_swap(__float_as_uint(ps), __float_as_uint(ps), false, false);
;     ps = __uint_as_float(rr[0]) + __uint_as_float(rr[1]); }
;   l_reg = l_reg * alpha + ps;
;     ...
;   PK4(p0, 0, pa0); PK4(p0, 8, pa1); PK4(p1, 0, pa2); PK4(p1, 8, pa3);
;     ...
; }
; template <bool WIN>
; __device__ __forceinline__ void qkt(f32x16& p0, f32x16& p1, const bf16_t* Ks, const bf16x8* qr, int r32, int hi, int dq) {
;   p0 = f32x16{}; p1 = f32x16{};
;   if (WIN) {
;     const int t = 4 * hi - dq + 128;
; #pragma unroll
;     for (int r = 0; r < 16; ++r) { const unsigned d0 = (unsigned)(t + (r & 3) + 8 * (r >> 2)), d1 = d0 + 32u;
;       p0[r] = d0 > 256u ? -1e30f : 0.f; p1[r] = d1 > 256u ? -1e30f : 0.f; }
;   }
; #pragma unroll
;   for (int d0 = 0; d0 < 8; ++d0) { int cb = (d0 * 16 + hi * 8) * 2;
;     bf16x8 b0 = *reinterpret_cast<const bf16x8*>((const char*)Ks + KSWZ(r32, cb));
;     bf16x8 b1 = *reinterpret_cast<const bf16x8*>((const char*)Ks + KSWZ(32 + r32, cb));
.LBB0_643:
	s_and_b32 s69, s68, 1
	s_xor_b32 s33, s69, 1
	s_lshl_b32 s33, s33, 14
	s_add_i32 s33, s35, s33
	s_mov_b64 s[0:1], 0x2000
	v_lshl_add_u64 v[254:255], s[22:23], 0, v[206:207]
	s_mov_b32 m0, s33
	s_nop 0
	global_load_lds_dwordx4 v[254:255], off
	v_lshl_add_u64 v[254:255], v[254:255], 0, s[0:1]
	s_add_i32 m0, s33, 0x2000
	s_nop 0
	global_load_lds_dwordx4 v[254:255], off
	v_lshl_add_u64 v[254:255], s[22:23], 0, v[204:205]
	s_add_i32 m0, s33, 0x400
	s_nop 0
	global_load_lds_dwordx4 v[254:255], off
	v_lshl_add_u64 v[254:255], v[254:255], 0, s[0:1]
	s_add_i32 m0, s33, 0x2400
	s_nop 0
	global_load_lds_dwordx4 v[254:255], off
	s_setprio 1
	s_lshl_b32 s0, s69, 14
	v_add3_u32 v0, s0, v209, v199
	ds_read_b128 v[130:133], v0
	ds_read_b128 v[134:137], v0 offset:8192
	v_add3_u32 v0, s0, v210, v199
	ds_read_b128 v[232:235], v0
	ds_read_b128 v[236:239], v0 offset:8192
	v_add3_u32 v0, s0, v211, v199
	ds_read_b128 v[246:249], v0
	ds_read_b128 v[250:253], v0 offset:8192
	s_waitcnt lgkmcnt(4)
	v_mfma_f32_32x32x16_bf16 v[146:161], v[130:133], v[162:165], 0
	v_mfma_f32_32x32x16_bf16 v[130:145], v[134:137], v[162:165], 0
	s_waitcnt lgkmcnt(2)
	v_mfma_f32_32x32x16_bf16 v[146:161], v[232:235], v[166:169], v[146:161]
	v_mfma_f32_32x32x16_bf16 v[130:145], v[236:239], v[166:169], v[130:145]
	v_add3_u32 v0, s0, v212, v199
	ds_read_b128 v[232:235], v0
	ds_read_b128 v[236:239], v0 offset:8192
	s_waitcnt lgkmcnt(2)
	v_mfma_f32_32x32x16_bf16 v[146:161], v[246:249], v[170:173], v[146:161]
	v_mfma_f32_32x32x16_bf16 v[130:145], v[250:253], v[170:173], v[130:145]
	v_add3_u32 v0, s0, v213, v199
	ds_read_b128 v[246:249], v0
	ds_read_b128 v[250:253], v0 offset:8192
	s_waitcnt lgkmcnt(2)
	v_mfma_f32_32x32x16_bf16 v[146:161], v[232:235], v[174:177], v[146:161]
	v_mfma_f32_32x32x16_bf16 v[130:145], v[236:239], v[174:177], v[130:145]
	v_add3_u32 v0, s0, v214, v199
	ds_read_b128 v[232:235], v0
	ds_read_b128 v[236:239], v0 offset:8192
	s_waitcnt lgkmcnt(2)
	v_mfma_f32_32x32x16_bf16 v[146:161], v[246:249], v[178:181], v[146:161]
	v_mfma_f32_32x32x16_bf16 v[130:145], v[250:253], v[178:181], v[130:145]
	v_add3_u32 v0, s0, v215, v199
	ds_read_b128 v[246:249], v0
	ds_read_b128 v[250:253], v0 offset:8192
	s_waitcnt lgkmcnt(2)
	v_mfma_f32_32x32x16_bf16 v[146:161], v[232:235], v[182:185], v[146:161]
	v_mfma_f32_32x32x16_bf16 v[130:145], v[236:239], v[182:185], v[130:145]
	v_add3_u32 v0, s0, v216, v199
	ds_read_b128 v[232:235], v0
	ds_read_b128 v[236:239], v0 offset:8192
	s_waitcnt lgkmcnt(2)
	v_mfma_f32_32x32x16_bf16 v[146:161], v[246:249], v[186:189], v[146:161]
	v_mfma_f32_32x32x16_bf16 v[130:145], v[250:253], v[186:189], v[130:145]
	s_waitcnt lgkmcnt(0)
	v_mfma_f32_32x32x16_bf16 v[146:161], v[232:235], v[190:193], v[146:161]
	v_mfma_f32_32x32x16_bf16 v[130:145], v[236:239], v[190:193], v[130:145]
	s_setprio 0
	s_nop 7
	s_nop 3
	v_max3_f32 v0, v146, v147, v148
	v_max3_f32 v231, v130, v131, v132
	v_max3_f32 v0, v0, v149, v150
	v_max3_f32 v231, v231, v133, v134
	v_max3_f32 v0, v0, v151, v152
	v_max3_f32 v231, v231, v135, v136
	v_max3_f32 v0, v0, v153, v154
	v_max3_f32 v231, v231, v137, v138
	v_max3_f32 v0, v0, v155, v156
	v_max3_f32 v231, v231, v139, v140
	v_max3_f32 v0, v0, v157, v158
	v_max3_f32 v231, v231, v141, v142
	v_max3_f32 v0, v0, v159, v160
	v_max3_f32 v231, v231, v143, v144
	v_max3_f32 v0, v0, v161, v231
	v_max_f32_e32 v0, v0, v145
	v_mov_b32_e32 v231, v0
	s_nop 1
	v_permlane32_swap_b32_e32 v0, v231
	v_max_f32_e32 v0, v0, v231
	v_sub_f32_e32 v231, v0, v229
	s_mov_b32 s0, 0x42b504f3
	v_cmp_ge_f32_e32 vcc, s0, v231
	v_max_f32_e32 v232, v229, v0
	s_cmp_eq_u64 vcc, exec
	s_cselect_b64 vcc, -1, 0
	v_sub_f32_e32 v0, v229, v232
	v_cndmask_b32_e32 v229, v232, v229, vcc
	v_mul_f32_e32 v231, 0xbe0293ee, v229
	v_fmamk_f32 v146, v146, 0x3e0293ee, v231
	v_fmamk_f32 v147, v147, 0x3e0293ee, v231
	v_fmamk_f32 v148, v148, 0x3e0293ee, v231
	v_fmamk_f32 v149, v149, 0x3e0293ee, v231
	v_fmamk_f32 v150, v150, 0x3e0293ee, v231
	v_fmamk_f32 v151, v151, 0x3e0293ee, v231
	v_fmamk_f32 v152, v152, 0x3e0293ee, v231
	v_fmamk_f32 v153, v153, 0x3e0293ee, v231
	v_fmamk_f32 v154, v154, 0x3e0293ee, v231
	v_fmamk_f32 v155, v155, 0x3e0293ee, v231
	v_fmamk_f32 v156, v156, 0x3e0293ee, v231
	v_fmamk_f32 v157, v157, 0x3e0293ee, v231
	v_fmamk_f32 v158, v158, 0x3e0293ee, v231
	v_fmamk_f32 v159, v159, 0x3e0293ee, v231
	v_fmamk_f32 v160, v160, 0x3e0293ee, v231
	v_fmamk_f32 v161, v161, 0x3e0293ee, v231
	v_fmamk_f32 v130, v130, 0x3e0293ee, v231
	v_fmamk_f32 v131, v131, 0x3e0293ee, v231
	v_fmamk_f32 v132, v132, 0x3e0293ee, v231
	v_fmamk_f32 v133, v133, 0x3e0293ee, v231
	v_fmamk_f32 v134, v134, 0x3e0293ee, v231
	v_fmamk_f32 v135, v135, 0x3e0293ee, v231
	v_fmamk_f32 v136, v136, 0x3e0293ee, v231
	v_fmamk_f32 v137, v137, 0x3e0293ee, v231
	v_fmamk_f32 v138, v138, 0x3e0293ee, v231
	v_fmamk_f32 v139, v139, 0x3e0293ee, v231
	v_fmamk_f32 v140, v140, 0x3e0293ee, v231
	v_fmamk_f32 v141, v141, 0x3e0293ee, v231
	v_fmamk_f32 v142, v142, 0x3e0293ee, v231
	v_fmamk_f32 v143, v143, 0x3e0293ee, v231
	v_fmamk_f32 v144, v144, 0x3e0293ee, v231
	v_fmac_f32_e32 v231, 0x3e0293ee, v145
	v_exp_f32_e32 v145, v146
	v_exp_f32_e32 v146, v147
	v_exp_f32_e32 v147, v148
	v_exp_f32_e32 v148, v149
	v_exp_f32_e32 v149, v150
	v_exp_f32_e32 v150, v151
	v_exp_f32_e32 v151, v152
	v_exp_f32_e32 v152, v153
	v_exp_f32_e32 v153, v154
	v_exp_f32_e32 v154, v155
	v_exp_f32_e32 v155, v156
	v_exp_f32_e32 v156, v157
	v_exp_f32_e32 v157, v158
	v_exp_f32_e32 v158, v159
	v_exp_f32_e32 v159, v160
	v_exp_f32_e32 v160, v161
	v_exp_f32_e32 v161, v134
	v_add_f32_e32 v134, v146, v145
	v_add_f32_e32 v134, v147, v134
	v_add_f32_e32 v134, v148, v134
	v_add_f32_e32 v134, v149, v134
; __device__ __forceinline__ void finishSM(f32x16& p0, f32x16& p1, float alpha, float& l_reg, bf16x8& pa0, bf16x8& pa1, bf16x8& pa2, bf16x8& pa3) {
; #pragma unroll
;   for (int r = 0; r < 16; ++r) p1[r] = __builtin_amdgcn_exp2f(p1[r]);
;   float ps = 0;
; #pragma unroll
;   for (int r = 0; r < 16; ++r) ps += p0[r];
; #pragma unroll
;   for (int r = 0; r < 16; ++r) ps += p1[r];
;   { auto rr = __builtin_amdgcn_permlane32_swap(__float_as_uint(ps), __float_as_uint(ps), false, false);
;     ps = __uint_as_float(rr[0]) + __uint_as_float(rr[1]); }
;   l_reg = l_reg * alpha + ps;
;     ...
;   PK4(p0, 0, pa0); PK4(p0, 8, pa1); PK4(p1, 0, pa2); PK4(p1, 8, pa3);
;     ...
; }
	v_add_f32_e32 v134, v150, v134
	v_add_f32_e32 v134, v151, v134
	v_add_f32_e32 v134, v152, v134
	v_add_f32_e32 v134, v153, v134
	v_add_f32_e32 v134, v154, v134
	v_add_f32_e32 v134, v155, v134
	v_add_f32_e32 v134, v156, v134
	v_exp_f32_e32 v130, v130
	v_add_f32_e32 v134, v157, v134
	v_exp_f32_e32 v131, v131
	v_add_f32_e32 v134, v158, v134
	v_exp_f32_e32 v132, v132
	v_add_f32_e32 v134, v159, v134
	v_exp_f32_e32 v133, v133
	v_add_f32_e32 v134, v160, v134
	v_add_f32_e32 v134, v130, v134
	v_exp_f32_e32 v233, v135
	v_add_f32_e32 v134, v131, v134
	v_exp_f32_e32 v234, v136
	v_add_f32_e32 v134, v132, v134
	v_exp_f32_e32 v235, v137
	v_add_f32_e32 v134, v133, v134
	v_exp_f32_e32 v138, v138
	v_add_f32_e32 v134, v161, v134
	v_exp_f32_e32 v139, v139
	v_add_f32_e32 v134, v233, v134
	v_exp_f32_e32 v140, v140
	v_add_f32_e32 v134, v234, v134
	v_exp_f32_e32 v141, v141
	v_add_f32_e32 v134, v235, v134
	v_exp_f32_e32 v236, v142
	v_add_f32_e32 v134, v138, v134
	v_exp_f32_e32 v237, v143
	v_add_f32_e32 v134, v139, v134
	v_exp_f32_e32 v238, v144
	v_add_f32_e32 v134, v140, v134
	v_mul_f32_e32 v0, 0x3e0293ee, v0
	v_exp_f32_e32 v239, v231
	v_add_f32_e32 v134, v141, v134
	v_exp_f32_e32 v0, v0
	v_add_f32_e32 v134, v236, v134
	v_add_f32_e32 v134, v237, v134
	v_add_f32_e32 v134, v238, v134
	v_add_f32_e32 v231, v239, v134
	v_cndmask_b32_e64 v0, v0, 1.0, vcc
	v_mov_b32_e32 v232, v231
	v_cvt_pk_bf16_f32 v134, v145, v146
	v_cvt_pk_bf16_f32 v135, v147, v148
	v_cvt_pk_bf16_f32 v136, v149, v150
	v_cvt_pk_bf16_f32 v137, v151, v152
	v_cvt_pk_bf16_f32 v142, v153, v154
	v_cvt_pk_bf16_f32 v143, v155, v156
	v_cvt_pk_bf16_f32 v144, v157, v158
	v_cvt_pk_bf16_f32 v145, v159, v160
	v_cvt_pk_bf16_f32 v130, v130, v131
	v_cvt_pk_bf16_f32 v131, v132, v133
	v_cvt_pk_bf16_f32 v132, v161, v233
	v_cvt_pk_bf16_f32 v133, v234, v235
	v_cvt_pk_bf16_f32 v138, v138, v139
	v_cvt_pk_bf16_f32 v139, v140, v141
	v_cvt_pk_bf16_f32 v140, v236, v237
	v_cvt_pk_bf16_f32 v141, v238, v239
	v_permlane32_swap_b32_e32 v231, v232
	v_permlane32_swap_b32_e32 v134, v136
	v_permlane32_swap_b32_e32 v135, v137
	v_permlane32_swap_b32_e32 v142, v144
	v_permlane32_swap_b32_e32 v143, v145
	v_permlane32_swap_b32_e32 v130, v132
	v_permlane32_swap_b32_e32 v131, v133
	v_permlane32_swap_b32_e32 v138, v140
	v_permlane32_swap_b32_e32 v139, v141
	v_cmp_gt_f32_e32 vcc, 1.0, v0
	s_cbranch_vccz .LBB0_649
	s_and_saveexec_b64 s[0:1], s[6:7]
	ds_write_b32 v228, v0 offset:128
	s_or_b64 exec, exec, s[0:1]
	s_waitcnt lgkmcnt(0)
	v_add_u32_e32 v146, s67, v223
	ds_read_b128 v[158:161], v146 offset:224
	ds_read_b128 v[154:157], v146 offset:192
	ds_read_b128 v[150:153], v146 offset:160
	ds_read_b128 v[146:149], v146 offset:128
	s_waitcnt lgkmcnt(0)
	v_pk_mul_f32 v[126:127], v[126:127], v[158:159]
	v_pk_mul_f32 v[122:123], v[122:123], v[154:155]
	v_pk_mul_f32 v[118:119], v[118:119], v[150:151]
	v_pk_mul_f32 v[128:129], v[128:129], v[160:161]
	v_pk_mul_f32 v[124:125], v[124:125], v[156:157]
	v_pk_mul_f32 v[120:121], v[120:121], v[152:153]
	v_pk_mul_f32 v[116:117], v[116:117], v[148:149]
	v_pk_mul_f32 v[114:115], v[114:115], v[146:147]
	v_pk_mul_f32 v[110:111], v[110:111], v[158:159]
	v_pk_mul_f32 v[106:107], v[106:107], v[154:155]
	v_pk_mul_f32 v[102:103], v[102:103], v[150:151]
	v_pk_mul_f32 v[112:113], v[112:113], v[160:161]
	v_pk_mul_f32 v[108:109], v[108:109], v[156:157]
	v_pk_mul_f32 v[104:105], v[104:105], v[152:153]
	v_pk_mul_f32 v[100:101], v[100:101], v[148:149]
	v_pk_mul_f32 v[98:99], v[98:99], v[146:147]
	v_pk_mul_f32 v[94:95], v[94:95], v[158:159]
	v_pk_mul_f32 v[90:91], v[90:91], v[154:155]
	v_pk_mul_f32 v[86:87], v[86:87], v[150:151]
	v_pk_mul_f32 v[96:97], v[96:97], v[160:161]
	v_pk_mul_f32 v[92:93], v[92:93], v[156:157]
	v_pk_mul_f32 v[88:89], v[88:89], v[152:153]
	v_pk_mul_f32 v[84:85], v[84:85], v[148:149]
	v_pk_mul_f32 v[82:83], v[82:83], v[146:147]
	v_pk_mul_f32 v[78:79], v[78:79], v[158:159]
	v_pk_mul_f32 v[74:75], v[74:75], v[154:155]
	v_pk_mul_f32 v[70:71], v[70:71], v[150:151]
	v_pk_mul_f32 v[80:81], v[80:81], v[160:161]
	v_pk_mul_f32 v[76:77], v[76:77], v[156:157]
	v_pk_mul_f32 v[72:73], v[72:73], v[152:153]
	v_pk_mul_f32 v[68:69], v[68:69], v[148:149]
	v_pk_mul_f32 v[66:67], v[66:67], v[146:147]
	v_pk_mul_f32 v[62:63], v[62:63], v[158:159]
	v_pk_mul_f32 v[58:59], v[58:59], v[154:155]
	v_pk_mul_f32 v[54:55], v[54:55], v[150:151]
	v_pk_mul_f32 v[64:65], v[64:65], v[160:161]
	v_pk_mul_f32 v[60:61], v[60:61], v[156:157]
	v_pk_mul_f32 v[56:57], v[56:57], v[152:153]
	v_pk_mul_f32 v[52:53], v[52:53], v[148:149]
	v_pk_mul_f32 v[50:51], v[50:51], v[146:147]
	v_pk_mul_f32 v[46:47], v[46:47], v[158:159]
	v_pk_mul_f32 v[42:43], v[42:43], v[154:155]
	v_pk_mul_f32 v[38:39], v[38:39], v[150:151]
	v_pk_mul_f32 v[48:49], v[48:49], v[160:161]
	v_pk_mul_f32 v[44:45], v[44:45], v[156:157]
	v_pk_mul_f32 v[40:41], v[40:41], v[152:153]
	v_pk_mul_f32 v[36:37], v[36:37], v[148:149]
	v_pk_mul_f32 v[34:35], v[34:35], v[146:147]
	v_pk_mul_f32 v[30:31], v[30:31], v[158:159]
	v_pk_mul_f32 v[26:27], v[26:27], v[154:155]
	v_pk_mul_f32 v[22:23], v[22:23], v[150:151]
	v_pk_mul_f32 v[32:33], v[32:33], v[160:161]
	v_pk_mul_f32 v[28:29], v[28:29], v[156:157]
	v_pk_mul_f32 v[24:25], v[24:25], v[152:153]
	v_pk_mul_f32 v[20:21], v[20:21], v[148:149]
	v_pk_mul_f32 v[18:19], v[18:19], v[146:147]
	v_pk_mul_f32 v[14:15], v[14:15], v[158:159]
	v_pk_mul_f32 v[10:11], v[10:11], v[154:155]
	v_pk_mul_f32 v[6:7], v[6:7], v[150:151]
	v_pk_mul_f32 v[16:17], v[16:17], v[160:161]
	v_pk_mul_f32 v[12:13], v[12:13], v[156:157]
	v_pk_mul_f32 v[8:9], v[8:9], v[152:153]
	v_pk_mul_f32 v[4:5], v[4:5], v[148:149]
	v_pk_mul_f32 v[2:3], v[2:3], v[146:147]
; #define SBAR() __builtin_amdgcn_sched_barrier(0)
; #define RESC8(a) do { if (__any((a) < 1.f)) { if (hi == 0) al_l[r32] = (a); asm volatile("s_waitcnt lgkmcnt(0)" ::: "memory"); \
;     _Pragma("unroll") for (int d = 0; d < 8; ++d) _Pragma("unroll") for (int r = 0; r < 16; ++r) o[d][r] *= al_l[crow(r, hi)]; } } while (0)
; template <int D0> __device__ __forceinline__ void pv_one(f32x16& od, int vb, bf16x8 pa0, bf16x8 pa1, bf16x8 pa2, bf16x8 pa3) {
;   const s16x4 l0 = tr_read<v_rd_off(D0, 0, 0)>(vb), h0 = tr_read<v_rd_off(D0, 0, 1)>(vb), l1 = tr_read<v_rd_off(D0, 1, 0)>(vb), h1 = tr_read<v_rd_off(D0, 1, 1)>(vb);
;   const s16x4 l2 = tr_read<v_rd_off(D0, 2, 0)>(vb), h2 = tr_read<v_rd_off(D0, 2, 1)>(vb), l3 = tr_read<v_rd_off(D0, 3, 0)>(vb), h3 = tr_read<v_rd_off(D0, 3, 1)>(vb);
;   asm volatile("s_waitcnt lgkmcnt(0)" ::: "memory"); SBAR();
;     ...
;   od = __builtin_amdgcn_mfma_f32_32x32x16_bf16(pa0, PK(l0, h0), od, 0, 0, 0);
;   od = __builtin_amdgcn_mfma_f32_32x32x16_bf16(pa1, PK(l1, h1), od, 0, 0, 0);
;   od = __builtin_amdgcn_mfma_f32_32x32x16_bf16(pa2, PK(l2, h2), od, 0, 0, 0);
;   od = __builtin_amdgcn_mfma_f32_32x32x16_bf16(pa3, PK(l3, h3), od, 0, 0, 0);
;     ...
; }
; __device__ __forceinline__ void pv_d0(f32x16* o, int vb, bf16x8 pa0, bf16x8 pa1, bf16x8 pa2, bf16x8 pa3) {
;   pv_one<0>(o[0], vb, pa0, pa1, pa2, pa3); pv_one<1>(o[1], vb, pa0, pa1, pa2, pa3); pv_one<2>(o[2], vb, pa0, pa1, pa2, pa3); pv_one<3>(o[3], vb, pa0, pa1, pa2, pa3);
; }
; template <int LDO>
; __device__ __forceinline__ void attn_unit_dv(const bf16_t* __restrict__ Qb, const bf16_t* __restrict__ Kh, const bf16_t* __restrict__ Vh, bf16_t* __restrict__ Ob, int NT, char* lds, LAS3 unsigned char* ldsl) {
;     ...
;     if (t + 1 < NT) DMA_KV(t + 1, buf ^ 1);
;     SBAR();
;     partialSM<false>(p0, p1, m_reg, mn, alpha);
;     finishSM(p0, p1, alpha, l_reg, pa0, pa1, pa2, pa3);
;     RESC8(alpha);
;     SBAR();
;     pv_d0(o, vb0 + buf * 32768, pa0, pa1, pa2, pa3);
;     pv_d0(o + 4, vb0 + buf * 32768 + 16384, pa0, pa1, pa2, pa3);
;     asm volatile("s_waitcnt vmcnt(0) lgkmcnt(0)" ::: "memory"); __builtin_amdgcn_s_barrier(); asm volatile("" ::: "memory");
.LBB0_649:
	s_waitcnt vmcnt(8)
	s_barrier
	s_lshl_b32 s0, s101, 15
	s_add_i32 s33, s66, s0
	v_lshl_add_u64 v[254:255], s[22:23], 0, v[202:203]
	s_mov_b64 s[0:1], 0x33e10000
	v_lshl_add_u64 v[254:255], v[254:255], 0, s[0:1]
	s_add_i32 m0, s33, 0x8000
	s_mov_b64 s[0:1], 0x80
	global_load_lds_dwordx4 v[254:255], off
	v_lshl_add_u64 v[254:255], v[254:255], 0, s[0:1]
	s_add_i32 m0, s33, 0x8400
	s_mov_b64 s[0:1], 0x780
	global_load_lds_dwordx4 v[254:255], off
	v_lshl_add_u64 v[254:255], v[254:255], 0, s[0:1]
	s_add_i32 m0, s33, 0x8800
	s_mov_b64 s[0:1], 0x80
	global_load_lds_dwordx4 v[254:255], off
	v_lshl_add_u64 v[254:255], v[254:255], 0, s[0:1]
	s_add_i32 m0, s33, 0x8c00
	s_nop 0
	global_load_lds_dwordx4 v[254:255], off
	v_add_f32_e32 v146, v231, v232
	v_fmac_f32_e32 v146, v230, v0
	s_add_i32 s68, s68, 1
	v_lshl_add_u32 v0, s98, 15, v224
	ds_read_b64_tr_b16 v[148:149], v0 offset:0
	ds_read_b64_tr_b16 v[150:151], v0 offset:0x800
	ds_read_b64_tr_b16 v[152:153], v0 offset:0x1000
	ds_read_b64_tr_b16 v[154:155], v0 offset:0x1800
	ds_read_b64_tr_b16 v[156:157], v0 offset:0x2000
	ds_read_b64_tr_b16 v[158:159], v0 offset:0x2800
	ds_read_b64_tr_b16 v[230:231], v0 offset:0x3000
	ds_read_b64_tr_b16 v[232:233], v0 offset:0x3800
	s_waitcnt lgkmcnt(0)
	s_nop 0
	v_mfma_f32_32x32x16_bf16 v[114:129], v[134:137], v[148:151], v[114:129]
	ds_read_b64_tr_b16 v[148:149], v0 offset:0x200
	ds_read_b64_tr_b16 v[150:151], v0 offset:0xa00
	v_mfma_f32_32x32x16_bf16 v[114:129], v[142:145], v[152:155], v[114:129]
	ds_read_b64_tr_b16 v[152:153], v0 offset:0x1200
	ds_read_b64_tr_b16 v[154:155], v0 offset:0x1a00
	v_mfma_f32_32x32x16_bf16 v[114:129], v[130:133], v[156:159], v[114:129]
	ds_read_b64_tr_b16 v[156:157], v0 offset:0x2200
	ds_read_b64_tr_b16 v[158:159], v0 offset:0x2a00
	ds_read_b64_tr_b16 v[234:235], v0 offset:0x3200
	ds_read_b64_tr_b16 v[236:237], v0 offset:0x3a00
	s_waitcnt lgkmcnt(0)
	v_mfma_f32_32x32x16_bf16 v[114:129], v[138:141], v[230:233], v[114:129]
	v_mfma_f32_32x32x16_bf16 v[98:113], v[134:137], v[148:151], v[98:113]
	ds_read_b64_tr_b16 v[148:149], v0 offset:0x400
	ds_read_b64_tr_b16 v[150:151], v0 offset:0xc00
	v_mfma_f32_32x32x16_bf16 v[98:113], v[142:145], v[152:155], v[98:113]
	ds_read_b64_tr_b16 v[152:153], v0 offset:0x1400
	ds_read_b64_tr_b16 v[154:155], v0 offset:0x1c00
	v_mfma_f32_32x32x16_bf16 v[98:113], v[130:133], v[156:159], v[98:113]
	ds_read_b64_tr_b16 v[156:157], v0 offset:0x2400
	ds_read_b64_tr_b16 v[158:159], v0 offset:0x2c00
	ds_read_b64_tr_b16 v[230:231], v0 offset:0x3400
	ds_read_b64_tr_b16 v[232:233], v0 offset:0x3c00
	s_waitcnt lgkmcnt(0)
	v_mfma_f32_32x32x16_bf16 v[98:113], v[138:141], v[234:237], v[98:113]
	v_mfma_f32_32x32x16_bf16 v[82:97], v[134:137], v[148:151], v[82:97]
	ds_read_b64_tr_b16 v[148:149], v0 offset:0x600
	ds_read_b64_tr_b16 v[150:151], v0 offset:0xe00
	v_mfma_f32_32x32x16_bf16 v[82:97], v[142:145], v[152:155], v[82:97]
	ds_read_b64_tr_b16 v[152:153], v0 offset:0x1600
	ds_read_b64_tr_b16 v[154:155], v0 offset:0x1e00
	v_mfma_f32_32x32x16_bf16 v[82:97], v[130:133], v[156:159], v[82:97]
	ds_read_b64_tr_b16 v[156:157], v0 offset:0x2600
	ds_read_b64_tr_b16 v[158:159], v0 offset:0x2e00
	ds_read_b64_tr_b16 v[234:235], v0 offset:0x3600
	ds_read_b64_tr_b16 v[236:237], v0 offset:0x3e00
	s_waitcnt lgkmcnt(0)
	v_mfma_f32_32x32x16_bf16 v[82:97], v[138:141], v[230:233], v[82:97]
	v_mfma_f32_32x32x16_bf16 v[66:81], v[134:137], v[148:151], v[66:81]
	v_add_u32_e32 v0, 0x4000, v0
	ds_read_b64_tr_b16 v[148:149], v0 offset:0
	ds_read_b64_tr_b16 v[150:151], v0 offset:0x800
	v_mfma_f32_32x32x16_bf16 v[66:81], v[142:145], v[152:155], v[66:81]
	ds_read_b64_tr_b16 v[152:153], v0 offset:0x1000
	ds_read_b64_tr_b16 v[154:155], v0 offset:0x1800
	v_mfma_f32_32x32x16_bf16 v[66:81], v[130:133], v[156:159], v[66:81]
	ds_read_b64_tr_b16 v[156:157], v0 offset:0x2000
	ds_read_b64_tr_b16 v[158:159], v0 offset:0x2800
	ds_read_b64_tr_b16 v[230:231], v0 offset:0x3000
	ds_read_b64_tr_b16 v[232:233], v0 offset:0x3800
	s_waitcnt lgkmcnt(0)
	v_mfma_f32_32x32x16_bf16 v[66:81], v[138:141], v[234:237], v[66:81]
	v_mfma_f32_32x32x16_bf16 v[50:65], v[134:137], v[148:151], v[50:65]
	ds_read_b64_tr_b16 v[148:149], v0 offset:0x200
	ds_read_b64_tr_b16 v[150:151], v0 offset:0xa00
	v_mfma_f32_32x32x16_bf16 v[50:65], v[142:145], v[152:155], v[50:65]
	ds_read_b64_tr_b16 v[152:153], v0 offset:0x1200
	ds_read_b64_tr_b16 v[154:155], v0 offset:0x1a00
	v_mfma_f32_32x32x16_bf16 v[50:65], v[130:133], v[156:159], v[50:65]
	ds_read_b64_tr_b16 v[156:157], v0 offset:0x2200
	ds_read_b64_tr_b16 v[158:159], v0 offset:0x2a00
	ds_read_b64_tr_b16 v[234:235], v0 offset:0x3200
	ds_read_b64_tr_b16 v[236:237], v0 offset:0x3a00
	s_waitcnt lgkmcnt(0)
	v_mfma_f32_32x32x16_bf16 v[50:65], v[138:141], v[230:233], v[50:65]
	v_mfma_f32_32x32x16_bf16 v[34:49], v[134:137], v[148:151], v[34:49]
	ds_read_b64_tr_b16 v[148:149], v0 offset:0x400
	ds_read_b64_tr_b16 v[150:151], v0 offset:0xc00
	v_mfma_f32_32x32x16_bf16 v[34:49], v[142:145], v[152:155], v[34:49]
	ds_read_b64_tr_b16 v[152:153], v0 offset:0x1400
	ds_read_b64_tr_b16 v[154:155], v0 offset:0x1c00
	v_mfma_f32_32x32x16_bf16 v[34:49], v[130:133], v[156:159], v[34:49]
	ds_read_b64_tr_b16 v[156:157], v0 offset:0x2400
	ds_read_b64_tr_b16 v[158:159], v0 offset:0x2c00
	ds_read_b64_tr_b16 v[230:231], v0 offset:0x3400
	ds_read_b64_tr_b16 v[232:233], v0 offset:0x3c00
	s_waitcnt lgkmcnt(0)
	v_mfma_f32_32x32x16_bf16 v[34:49], v[138:141], v[234:237], v[34:49]
	v_mfma_f32_32x32x16_bf16 v[18:33], v[134:137], v[148:151], v[18:33]
	ds_read_b64_tr_b16 v[148:149], v0 offset:0x600
	ds_read_b64_tr_b16 v[150:151], v0 offset:0xe00
	v_mfma_f32_32x32x16_bf16 v[18:33], v[142:145], v[152:155], v[18:33]
	ds_read_b64_tr_b16 v[152:153], v0 offset:0x1600
	ds_read_b64_tr_b16 v[154:155], v0 offset:0x1e00
	v_mfma_f32_32x32x16_bf16 v[18:33], v[130:133], v[156:159], v[18:33]
	ds_read_b64_tr_b16 v[156:157], v0 offset:0x2600
	ds_read_b64_tr_b16 v[158:159], v0 offset:0x2e00
	ds_read_b64_tr_b16 v[234:235], v0 offset:0x3600
	ds_read_b64_tr_b16 v[236:237], v0 offset:0x3e00
	s_waitcnt lgkmcnt(0)
	v_mfma_f32_32x32x16_bf16 v[18:33], v[138:141], v[230:233], v[18:33]
	v_mfma_f32_32x32x16_bf16 v[2:17], v[134:137], v[148:151], v[2:17]
	s_mov_b32 s98, s100
	s_mov_b32 s100, s101
	s_add_i32 s101, s101, 1
	s_cmp_eq_u32 s101, 3
	s_cselect_b32 s101, 0, s101
	s_mov_b64 s[0:1], 0x8000
	v_lshl_add_u64 v[202:203], v[202:203], 0, s[0:1]
	v_lshl_add_u64 v[204:205], v[204:205], 0, s[64:65]
	v_lshl_add_u64 v[206:207], v[206:207], 0, s[64:65]
	s_waitcnt vmcnt(4) lgkmcnt(0)
	s_barrier
	v_mfma_f32_32x32x16_bf16 v[2:17], v[142:145], v[152:155], v[2:17]
	s_cmpk_eq_i32 s68, 0x100
	v_mfma_f32_32x32x16_bf16 v[2:17], v[130:133], v[156:159], v[2:17]
	v_mfma_f32_32x32x16_bf16 v[2:17], v[138:141], v[234:237], v[2:17]
	s_cbranch_scc1 .LBB0_651
	v_mov_b32_e32 v230, v146
	s_branch .LBB0_643

; #define SBAR() __builtin_amdgcn_sched_barrier(0)
; #define RESC8(a) do { if (__any((a) < 1.f)) { if (hi == 0) al_l[r32] = (a); asm volatile("s_waitcnt lgkmcnt(0)" ::: "memory"); \
;     _Pragma("unroll") for (int d = 0; d < 8; ++d) _Pragma("unroll") for (int r = 0; r < 16; ++r) o[d][r] *= al_l[crow(r, hi)]; } } while (0)
; template <int D0> __device__ __forceinline__ void pv_one(f32x16& od, int vb, bf16x8 pa0, bf16x8 pa1, bf16x8 pa2, bf16x8 pa3) {
;   const s16x4 l0 = tr_read<v_rd_off(D0, 0, 0)>(vb), h0 = tr_read<v_rd_off(D0, 0, 1)>(vb), l1 = tr_read<v_rd_off(D0, 1, 0)>(vb), h1 = tr_read<v_rd_off(D0, 1, 1)>(vb);
;   const s16x4 l2 = tr_read<v_rd_off(D0, 2, 0)>(vb), h2 = tr_read<v_rd_off(D0, 2, 1)>(vb), l3 = tr_read<v_rd_off(D0, 3, 0)>(vb), h3 = tr_read<v_rd_off(D0, 3, 1)>(vb);
;   asm volatile("s_waitcnt lgkmcnt(0)" ::: "memory"); SBAR();
;     ...
;   od = __builtin_amdgcn_mfma_f32_32x32x16_bf16(pa0, PK(l0, h0), od, 0, 0, 0);
;   od = __builtin_amdgcn_mfma_f32_32x32x16_bf16(pa1, PK(l1, h1), od, 0, 0, 0);
;   od = __builtin_amdgcn_mfma_f32_32x32x16_bf16(pa2, PK(l2, h2), od, 0, 0, 0);
;   od = __builtin_amdgcn_mfma_f32_32x32x16_bf16(pa3, PK(l3, h3), od, 0, 0, 0);
;     ...
; }
; __device__ __forceinline__ void pv_d0(f32x16* o, int vb, bf16x8 pa0, bf16x8 pa1, bf16x8 pa2, bf16x8 pa3) {
;   pv_one<0>(o[0], vb, pa0, pa1, pa2, pa3); pv_one<1>(o[1], vb, pa0, pa1, pa2, pa3); pv_one<2>(o[2], vb, pa0, pa1, pa2, pa3); pv_one<3>(o[3], vb, pa0, pa1, pa2, pa3);
; }
; template <int LDO>
; __device__ __forceinline__ void attn_unit_dv(const bf16_t* __restrict__ Qb, const bf16_t* __restrict__ Kh, const bf16_t* __restrict__ Vh, bf16_t* __restrict__ Ob, int NT, char* lds, LAS3 unsigned char* ldsl) {
;     ...
;     if (t + 1 < NT) DMA_KV(t + 1, buf ^ 1);
;     SBAR();
;     partialSM<false>(p0, p1, m_reg, mn, alpha);
;     finishSM(p0, p1, alpha, l_reg, pa0, pa1, pa2, pa3);
;     RESC8(alpha);
;     SBAR();
;     pv_d0(o, vb0 + buf * 32768, pa0, pa1, pa2, pa3);
;     pv_d0(o + 4, vb0 + buf * 32768 + 16384, pa0, pa1, pa2, pa3);
;     asm volatile("s_waitcnt vmcnt(0) lgkmcnt(0)" ::: "memory"); __builtin_amdgcn_s_barrier(); asm volatile("" ::: "memory");
.Lpl_649:
	s_waitcnt vmcnt(4)
	s_barrier
	s_lshl_b32 s0, s101, 15
	s_add_i32 s33, s66, s0
	v_lshl_add_u64 v[254:255], s[22:23], 0, v[202:203]
	s_mov_b64 s[0:1], 0x33e10000
	v_lshl_add_u64 v[254:255], v[254:255], 0, s[0:1]
	s_add_i32 m0, s33, 0x8000
	s_mov_b64 s[0:1], 0x80
	global_load_lds_dwordx4 v[254:255], off
	v_lshl_add_u64 v[254:255], v[254:255], 0, s[0:1]
	s_add_i32 m0, s33, 0x8400
	s_mov_b64 s[0:1], 0x780
	global_load_lds_dwordx4 v[254:255], off
	v_lshl_add_u64 v[254:255], v[254:255], 0, s[0:1]
	s_add_i32 m0, s33, 0x8800
	s_mov_b64 s[0:1], 0x80
	global_load_lds_dwordx4 v[254:255], off
	v_lshl_add_u64 v[254:255], v[254:255], 0, s[0:1]
	s_add_i32 m0, s33, 0x8c00
	s_nop 0
	global_load_lds_dwordx4 v[254:255], off
	v_add_f32_e32 v146, v231, v232
	v_fmac_f32_e32 v146, v230, v0
	s_add_i32 s68, s68, 1
	v_lshl_add_u32 v0, s98, 15, v224
	ds_read_b64_tr_b16 v[148:149], v0 offset:0
	ds_read_b64_tr_b16 v[150:151], v0 offset:0x800
	ds_read_b64_tr_b16 v[152:153], v0 offset:0x1000
	ds_read_b64_tr_b16 v[154:155], v0 offset:0x1800
	ds_read_b64_tr_b16 v[156:157], v0 offset:0x2000
	ds_read_b64_tr_b16 v[158:159], v0 offset:0x2800
	ds_read_b64_tr_b16 v[230:231], v0 offset:0x3000
	ds_read_b64_tr_b16 v[232:233], v0 offset:0x3800
	s_waitcnt lgkmcnt(0)
	s_nop 0
	v_mfma_f32_32x32x16_bf16 v[114:129], v[134:137], v[148:151], v[114:129]
	ds_read_b64_tr_b16 v[148:149], v0 offset:0x200
	ds_read_b64_tr_b16 v[150:151], v0 offset:0xa00
	v_mfma_f32_32x32x16_bf16 v[114:129], v[142:145], v[152:155], v[114:129]
	ds_read_b64_tr_b16 v[152:153], v0 offset:0x1200
	ds_read_b64_tr_b16 v[154:155], v0 offset:0x1a00
	v_mfma_f32_32x32x16_bf16 v[114:129], v[130:133], v[156:159], v[114:129]
	ds_read_b64_tr_b16 v[156:157], v0 offset:0x2200
	ds_read_b64_tr_b16 v[158:159], v0 offset:0x2a00
	ds_read_b64_tr_b16 v[234:235], v0 offset:0x3200
	ds_read_b64_tr_b16 v[236:237], v0 offset:0x3a00
	s_waitcnt lgkmcnt(0)
	v_mfma_f32_32x32x16_bf16 v[114:129], v[138:141], v[230:233], v[114:129]
	v_mfma_f32_32x32x16_bf16 v[98:113], v[134:137], v[148:151], v[98:113]
	ds_read_b64_tr_b16 v[148:149], v0 offset:0x400
	ds_read_b64_tr_b16 v[150:151], v0 offset:0xc00
	v_mfma_f32_32x32x16_bf16 v[98:113], v[142:145], v[152:155], v[98:113]
	ds_read_b64_tr_b16 v[152:153], v0 offset:0x1400
	ds_read_b64_tr_b16 v[154:155], v0 offset:0x1c00
	v_mfma_f32_32x32x16_bf16 v[98:113], v[130:133], v[156:159], v[98:113]
	ds_read_b64_tr_b16 v[156:157], v0 offset:0x2400
	ds_read_b64_tr_b16 v[158:159], v0 offset:0x2c00
	ds_read_b64_tr_b16 v[230:231], v0 offset:0x3400
	ds_read_b64_tr_b16 v[232:233], v0 offset:0x3c00
	s_waitcnt lgkmcnt(0)
	v_mfma_f32_32x32x16_bf16 v[98:113], v[138:141], v[234:237], v[98:113]
	v_mfma_f32_32x32x16_bf16 v[82:97], v[134:137], v[148:151], v[82:97]
	ds_read_b64_tr_b16 v[148:149], v0 offset:0x600
	ds_read_b64_tr_b16 v[150:151], v0 offset:0xe00
	v_mfma_f32_32x32x16_bf16 v[82:97], v[142:145], v[152:155], v[82:97]
	ds_read_b64_tr_b16 v[152:153], v0 offset:0x1600
	ds_read_b64_tr_b16 v[154:155], v0 offset:0x1e00
	v_mfma_f32_32x32x16_bf16 v[82:97], v[130:133], v[156:159], v[82:97]
	ds_read_b64_tr_b16 v[156:157], v0 offset:0x2600
	ds_read_b64_tr_b16 v[158:159], v0 offset:0x2e00
	ds_read_b64_tr_b16 v[234:235], v0 offset:0x3600
	ds_read_b64_tr_b16 v[236:237], v0 offset:0x3e00
	s_waitcnt lgkmcnt(0)
	v_mfma_f32_32x32x16_bf16 v[82:97], v[138:141], v[230:233], v[82:97]
	v_mfma_f32_32x32x16_bf16 v[66:81], v[134:137], v[148:151], v[66:81]
	v_add_u32_e32 v0, 0x4000, v0
	ds_read_b64_tr_b16 v[148:149], v0 offset:0
	ds_read_b64_tr_b16 v[150:151], v0 offset:0x800
	v_mfma_f32_32x32x16_bf16 v[66:81], v[142:145], v[152:155], v[66:81]
	ds_read_b64_tr_b16 v[152:153], v0 offset:0x1000
	ds_read_b64_tr_b16 v[154:155], v0 offset:0x1800
	v_mfma_f32_32x32x16_bf16 v[66:81], v[130:133], v[156:159], v[66:81]
	ds_read_b64_tr_b16 v[156:157], v0 offset:0x2000
	ds_read_b64_tr_b16 v[158:159], v0 offset:0x2800
	ds_read_b64_tr_b16 v[230:231], v0 offset:0x3000
	ds_read_b64_tr_b16 v[232:233], v0 offset:0x3800
	s_waitcnt lgkmcnt(0)
	v_mfma_f32_32x32x16_bf16 v[66:81], v[138:141], v[234:237], v[66:81]
	v_mfma_f32_32x32x16_bf16 v[50:65], v[134:137], v[148:151], v[50:65]
	ds_read_b64_tr_b16 v[148:149], v0 offset:0x200
	ds_read_b64_tr_b16 v[150:151], v0 offset:0xa00
	v_mfma_f32_32x32x16_bf16 v[50:65], v[142:145], v[152:155], v[50:65]
	ds_read_b64_tr_b16 v[152:153], v0 offset:0x1200
	ds_read_b64_tr_b16 v[154:155], v0 offset:0x1a00
	v_mfma_f32_32x32x16_bf16 v[50:65], v[130:133], v[156:159], v[50:65]
	ds_read_b64_tr_b16 v[156:157], v0 offset:0x2200
	ds_read_b64_tr_b16 v[158:159], v0 offset:0x2a00
	ds_read_b64_tr_b16 v[234:235], v0 offset:0x3200
	ds_read_b64_tr_b16 v[236:237], v0 offset:0x3a00
	s_waitcnt lgkmcnt(0)
	v_mfma_f32_32x32x16_bf16 v[50:65], v[138:141], v[230:233], v[50:65]
	v_mfma_f32_32x32x16_bf16 v[34:49], v[134:137], v[148:151], v[34:49]
	ds_read_b64_tr_b16 v[148:149], v0 offset:0x400
	ds_read_b64_tr_b16 v[150:151], v0 offset:0xc00
	v_mfma_f32_32x32x16_bf16 v[34:49], v[142:145], v[152:155], v[34:49]
	ds_read_b64_tr_b16 v[152:153], v0 offset:0x1400
	ds_read_b64_tr_b16 v[154:155], v0 offset:0x1c00
	v_mfma_f32_32x32x16_bf16 v[34:49], v[130:133], v[156:159], v[34:49]
	ds_read_b64_tr_b16 v[156:157], v0 offset:0x2400
	ds_read_b64_tr_b16 v[158:159], v0 offset:0x2c00
	ds_read_b64_tr_b16 v[230:231], v0 offset:0x3400
	ds_read_b64_tr_b16 v[232:233], v0 offset:0x3c00
	s_waitcnt lgkmcnt(0)
	v_mfma_f32_32x32x16_bf16 v[34:49], v[138:141], v[234:237], v[34:49]
	v_mfma_f32_32x32x16_bf16 v[18:33], v[134:137], v[148:151], v[18:33]
	ds_read_b64_tr_b16 v[148:149], v0 offset:0x600
	ds_read_b64_tr_b16 v[150:151], v0 offset:0xe00
	v_mfma_f32_32x32x16_bf16 v[18:33], v[142:145], v[152:155], v[18:33]
	ds_read_b64_tr_b16 v[152:153], v0 offset:0x1600
	ds_read_b64_tr_b16 v[154:155], v0 offset:0x1e00
	v_mfma_f32_32x32x16_bf16 v[18:33], v[130:133], v[156:159], v[18:33]
	ds_read_b64_tr_b16 v[156:157], v0 offset:0x2600
	ds_read_b64_tr_b16 v[158:159], v0 offset:0x2e00
	ds_read_b64_tr_b16 v[234:235], v0 offset:0x3600
	ds_read_b64_tr_b16 v[236:237], v0 offset:0x3e00
	s_waitcnt lgkmcnt(0)
	v_mfma_f32_32x32x16_bf16 v[18:33], v[138:141], v[230:233], v[18:33]
	v_mfma_f32_32x32x16_bf16 v[2:17], v[134:137], v[148:151], v[2:17]
	s_mov_b32 s98, s100
	s_mov_b32 s100, s101
	s_add_i32 s101, s101, 1
	s_cmp_eq_u32 s101, 3
	s_cselect_b32 s101, 0, s101
	s_mov_b64 s[0:1], 0x8000
	v_lshl_add_u64 v[202:203], v[202:203], 0, s[0:1]
	v_lshl_add_u64 v[204:205], v[204:205], 0, s[64:65]
	v_lshl_add_u64 v[206:207], v[206:207], 0, s[64:65]
	s_waitcnt vmcnt(4) lgkmcnt(0)
	s_barrier
	v_mfma_f32_32x32x16_bf16 v[2:17], v[142:145], v[152:155], v[2:17]
	s_cmpk_eq_i32 s68, 0x100
	v_mfma_f32_32x32x16_bf16 v[2:17], v[130:133], v[156:159], v[2:17]
	v_mfma_f32_32x32x16_bf16 v[2:17], v[138:141], v[234:237], v[2:17]
	s_cbranch_scc1 .LBB0_651
	v_mov_b32_e32 v230, v146
	s_branch .Lpl_top
